# grid half 1 converts all later-layer weights (second batch at the end of its phase 1), half 0 none: halves run ~48us apart from layer 0 on, no global barrier at phase 4
# speedup vs baseline: 1.0296x; 1.0174x over previous
.LBB0_931:
	v_readlane_b32 s4, v255, 61
	s_mov_b64 s[2:3], -1
	s_cmp_lg_u32 s54, 1
	s_cselect_b32 s4, 0, s4
	s_cmp_eq_u32 s4, 0
	s_cselect_b64 s[4:5], -1, 0
	s_andn2_b64 vcc, exec, s[4:5]
	s_mov_b64 s[4:5], 0
	s_cbranch_vccnz .LBB0_986

.LBB0_986:
	s_and_b64 vcc, exec, s[2:3]
	s_cbranch_vccz .LBB0_1001
	s_mov_b32 s98, 0
	s_movk_i32 s99, 0x1880
	v_mov_b32_e32 v0, v247
	s_nop 0
	v_readfirstlane_b32 s2, v0
	s_ashr_i32 s4, s2, 6
	v_readlane_b32 s2, v253, 6
	s_add_i32 s14, s4, s2
	s_add_i32 s14, s14, s98
	s_cmp_ge_i32 s14, s99
	s_cbranch_scc1 .Lph4_bar
	s_load_dwordx2 s[2:3], s[88:89], 0x8
	v_lshlrev_b32_e32 v1, 2, v0
	s_mulk_i32 s4, 0x4100
	v_bfe_u32 v65, v0, 4, 2
	v_and_b32_e32 v64, 60, v1
	v_bfe_u32 v73, v0, 3, 3
	v_lshlrev_b32_e32 v0, 3, v0
	s_add_i32 s4, s4, 0
	v_lshlrev_b32_e32 v1, 2, v64
	v_mul_u32_u24_e32 v2, 0x104, v65
	v_and_b32_e32 v0, 56, v0
	v_add3_u32 v72, s4, v1, v2
	v_mul_u32_u24_e32 v1, 0x104, v0
	v_lshlrev_b32_e32 v2, 2, v73
	v_add3_u32 v74, s4, v1, v2
	s_waitcnt lgkmcnt(0)
	s_add_u32 s4, s2, 0x4000
	v_lshlrev_b32_e32 v208, 1, v0
	s_addc_u32 s5, s3, 0
	v_lshl_add_u64 v[2:3], s[82:83], 0, v[208:209]
	s_mov_b64 s[6:7], 0x4000000
	v_lshl_add_u64 v[66:67], v[2:3], 0, s[6:7]
	s_add_u32 s6, s2, 0x2000
	s_addc_u32 s7, s3, 0
	s_mov_b64 s[8:9], 0x2000000
	s_cmp_lg_u64 s[2:3], 0
	v_or_b32_e32 v75, 8, v73
	v_or_b32_e32 v76, 16, v73
	v_or_b32_e32 v77, 24, v73
	v_or_b32_e32 v78, 32, v73
	v_or_b32_e32 v79, 40, v73
	v_or_b32_e32 v80, 48, v73
	v_or_b32_e32 v81, 56, v73
	v_lshl_add_u64 v[68:69], v[2:3], 0, s[8:9]
	s_cselect_b64 s[8:9], -1, 0
	v_lshlrev_b32_e32 v70, 1, v0
	s_branch .LBB0_992
